# baseline (speedup 1.0000x reference)
.Lmg_top:
	v_readfirstlane_b32 s10, v0
	s_nop 3
	s_mul_i32 s11, s12, 3
	s_add_i32 s10, s10, s11
	s_cmp_gt_i32 s10, s9
	s_cbranch_scc1 .Lmg_tail
	v_ashrrev_i32_e32 v10, 9, v0
	v_ashrrev_i32_e32 v11, 31, v10
	v_lshlrev_b64 v[12:13], 7, v[10:11]
	v_lshl_add_u64 v[14:15], v[10:11], 0, s[4:5]
	v_lshl_add_u64 v[16:17], v[10:11], 0, s[6:7]
	v_lshlrev_b64 v[10:11], 13, v[10:11]
	v_lshl_add_u64 v[26:27], v[2:3], 0, v[12:13]
	v_lshlrev_b64 v[18:19], 7, v[14:15]
	v_lshlrev_b64 v[20:21], 7, v[16:17]
	v_lshlrev_b64 v[14:15], 13, v[14:15]
	v_lshlrev_b64 v[16:17], 13, v[16:17]
	v_lshl_add_u64 v[12:13], v[6:7], 0, v[10:11]
	v_lshl_add_u64 v[28:29], v[4:5], 0, v[10:11]
	v_lshl_add_u64 v[30:31], v[8:9], 0, v[10:11]
	global_load_dwordx4 v[10:13], v[12:13], off
	v_lshl_add_u64 v[32:33], v[2:3], 0, v[18:19]
	v_lshl_add_u64 v[34:35], v[2:3], 0, v[20:21]
	v_lshl_add_u64 v[36:37], v[4:5], 0, v[14:15]
	v_lshl_add_u64 v[38:39], v[4:5], 0, v[16:17]
	global_load_dword v1, v[26:27], off
	global_load_dword v46, v[32:33], off
	global_load_dword v47, v[34:35], off
	global_load_dwordx4 v[14:17], v[28:29], off
	global_load_dwordx4 v[18:21], v[36:37], off
	global_load_dwordx4 v[22:25], v[38:39], off
	v_add_u32_e32 v60, s12, v0
	v_ashrrev_i32_e32 v70, 9, v60
	v_ashrrev_i32_e32 v71, 31, v70
	v_lshlrev_b64 v[72:73], 7, v[70:71]
	v_lshl_add_u64 v[74:75], v[70:71], 0, s[4:5]
	v_lshl_add_u64 v[76:77], v[70:71], 0, s[6:7]
	v_lshlrev_b64 v[70:71], 13, v[70:71]
	v_lshl_add_u64 v[86:87], v[2:3], 0, v[72:73]
	v_lshlrev_b64 v[78:79], 7, v[74:75]
	v_lshlrev_b64 v[80:81], 7, v[76:77]
	v_lshlrev_b64 v[74:75], 13, v[74:75]
	v_lshlrev_b64 v[76:77], 13, v[76:77]
	v_lshl_add_u64 v[72:73], v[6:7], 0, v[70:71]
	v_lshl_add_u64 v[88:89], v[4:5], 0, v[70:71]
	v_lshl_add_u64 v[90:91], v[8:9], 0, v[70:71]
	global_load_dwordx4 v[70:73], v[72:73], off
	v_lshl_add_u64 v[92:93], v[2:3], 0, v[78:79]
	v_lshl_add_u64 v[94:95], v[2:3], 0, v[80:81]
	v_lshl_add_u64 v[96:97], v[4:5], 0, v[74:75]
	v_lshl_add_u64 v[98:99], v[4:5], 0, v[76:77]
	global_load_dword v61, v[86:87], off
	global_load_dword v106, v[92:93], off
	global_load_dword v107, v[94:95], off
	global_load_dwordx4 v[74:77], v[88:89], off
	global_load_dwordx4 v[78:81], v[96:97], off
	global_load_dwordx4 v[82:85], v[98:99], off
	v_add_u32_e32 v120, s12, v60
	v_ashrrev_i32_e32 v130, 9, v120
	v_ashrrev_i32_e32 v131, 31, v130
	v_lshlrev_b64 v[132:133], 7, v[130:131]
	v_lshl_add_u64 v[134:135], v[130:131], 0, s[4:5]
	v_lshl_add_u64 v[136:137], v[130:131], 0, s[6:7]
	v_lshlrev_b64 v[130:131], 13, v[130:131]
	v_lshl_add_u64 v[146:147], v[2:3], 0, v[132:133]
	v_lshlrev_b64 v[138:139], 7, v[134:135]
	v_lshlrev_b64 v[140:141], 7, v[136:137]
	v_lshlrev_b64 v[134:135], 13, v[134:135]
	v_lshlrev_b64 v[136:137], 13, v[136:137]
	v_lshl_add_u64 v[132:133], v[6:7], 0, v[130:131]
	v_lshl_add_u64 v[148:149], v[4:5], 0, v[130:131]
	v_lshl_add_u64 v[150:151], v[8:9], 0, v[130:131]
	global_load_dwordx4 v[130:133], v[132:133], off
	v_lshl_add_u64 v[152:153], v[2:3], 0, v[138:139]
	v_lshl_add_u64 v[154:155], v[2:3], 0, v[140:141]
	v_lshl_add_u64 v[156:157], v[4:5], 0, v[134:135]
	v_lshl_add_u64 v[158:159], v[4:5], 0, v[136:137]
	global_load_dword v121, v[146:147], off
	global_load_dword v166, v[152:153], off
	global_load_dword v167, v[154:155], off
	global_load_dwordx4 v[134:137], v[148:149], off
	global_load_dwordx4 v[138:141], v[156:157], off
	global_load_dwordx4 v[142:145], v[158:159], off
	v_add_u32_e32 v180, s12, v120
	v_ashrrev_i32_e32 v190, 9, v180
	v_ashrrev_i32_e32 v191, 31, v190
	v_lshlrev_b64 v[192:193], 7, v[190:191]
	v_lshl_add_u64 v[194:195], v[190:191], 0, s[4:5]
	v_lshl_add_u64 v[196:197], v[190:191], 0, s[6:7]
	v_lshlrev_b64 v[190:191], 13, v[190:191]
	v_lshl_add_u64 v[206:207], v[2:3], 0, v[192:193]
	v_lshlrev_b64 v[198:199], 7, v[194:195]
	v_lshlrev_b64 v[200:201], 7, v[196:197]
	v_lshlrev_b64 v[194:195], 13, v[194:195]
	v_lshlrev_b64 v[196:197], 13, v[196:197]
	v_lshl_add_u64 v[192:193], v[6:7], 0, v[190:191]
	v_lshl_add_u64 v[208:209], v[4:5], 0, v[190:191]
	v_lshl_add_u64 v[210:211], v[8:9], 0, v[190:191]
	global_load_dwordx4 v[190:193], v[192:193], off
	v_lshl_add_u64 v[212:213], v[2:3], 0, v[198:199]
	v_lshl_add_u64 v[214:215], v[2:3], 0, v[200:201]
	v_lshl_add_u64 v[216:217], v[4:5], 0, v[194:195]
	v_lshl_add_u64 v[218:219], v[4:5], 0, v[196:197]
	global_load_dword v181, v[206:207], off
	global_load_dword v226, v[212:213], off
	global_load_dword v227, v[214:215], off
	global_load_dwordx4 v[194:197], v[208:209], off
	global_load_dwordx4 v[198:201], v[216:217], off
	global_load_dwordx4 v[202:205], v[218:219], off
	v_add_u32_e32 v0, s12, v180
	s_waitcnt vmcnt(27)
	v_and_b32_e32 v27, 0xffff0000, v10
	v_lshlrev_b32_e32 v26, 16, v10
	s_waitcnt vmcnt(24)
	v_max3_f32 v48, v1, v46, v47
	v_sub_f32_e32 v1, v1, v48
	v_and_b32_e32 v29, 0xffff0000, v11
	s_waitcnt vmcnt(21)
	v_and_b32_e32 v43, 0xffff0000, v24
	v_lshlrev_b32_e32 v42, 16, v24
	v_sub_f32_e32 v24, v46, v48
	v_lshlrev_b32_e32 v28, 16, v11
	v_and_b32_e32 v11, 0xffff0000, v12
	v_lshlrev_b32_e32 v10, 16, v12
	v_and_b32_e32 v33, 0xffff0000, v13
	v_lshlrev_b32_e32 v32, 16, v13
	v_and_b32_e32 v13, 0xffff0000, v14
	v_lshlrev_b32_e32 v12, 16, v18
	v_and_b32_e32 v35, 0xffff0000, v18
	v_lshlrev_b32_e32 v34, 16, v14
	v_and_b32_e32 v37, 0xffff0000, v22
	v_lshlrev_b32_e32 v36, 16, v22
	v_and_b32_e32 v39, 0xffff0000, v15
	v_lshlrev_b32_e32 v18, 16, v15
	v_and_b32_e32 v15, 0xffff0000, v23
	v_lshlrev_b32_e32 v14, 16, v23
	v_and_b32_e32 v23, 0xffff0000, v16
	v_lshlrev_b32_e32 v22, 16, v20
	v_and_b32_e32 v41, 0xffff0000, v20
	v_lshlrev_b32_e32 v40, 16, v16
	v_and_b32_e32 v45, 0xffff0000, v17
	v_lshlrev_b32_e32 v20, 16, v17
	v_and_b32_e32 v17, 0xffff0000, v25
	v_lshlrev_b32_e32 v16, 16, v25
	v_sub_f32_e32 v25, v47, v48
	v_mul_f32_e32 v1, 0x3fb8aa3b, v1
	v_mul_f32_e32 v24, 0x3fb8aa3b, v24
	v_mul_f32_e32 v46, 0x3fb8aa3b, v25
	v_exp_f32_e32 v25, v1
	v_exp_f32_e32 v24, v24
	v_exp_f32_e32 v1, v46
	v_lshlrev_b32_e32 v38, 16, v19
	v_and_b32_e32 v19, 0xffff0000, v19
	v_add_f32_e32 v46, v25, v24
	v_add_f32_e32 v46, v1, v46
	v_div_scale_f32 v47, s[10:11], v46, v46, 1.0
	v_rcp_f32_e32 v49, v47
	v_div_scale_f32 v48, vcc, 1.0, v46, 1.0
	v_lshlrev_b32_e32 v44, 16, v21
	v_fma_f32 v50, -v47, v49, 1.0
	v_fmac_f32_e32 v49, v50, v49
	v_mul_f32_e32 v50, v48, v49
	v_fma_f32 v51, -v47, v50, v48
	v_fmac_f32_e32 v50, v51, v49
	v_fma_f32 v47, -v47, v50, v48
	v_div_fmas_f32 v47, v47, v49, v50
	v_div_fixup_f32 v46, v47, v46, 1.0
	v_and_b32_e32 v21, 0xffff0000, v21
	v_pk_mul_f32 v[24:25], v[24:25], v[46:47] op_sel_hi:[1,0]
	v_mul_f32_e32 v48, v1, v46
	v_pk_mul_f32 v[34:35], v[24:25], v[34:35] op_sel:[1,0] op_sel_hi:[0,1]
	v_pk_mul_f32 v[18:19], v[24:25], v[18:19] op_sel:[1,0] op_sel_hi:[0,1]
	v_pk_mul_f32 v[40:41], v[24:25], v[40:41] op_sel:[1,0] op_sel_hi:[0,1]
	v_pk_mul_f32 v[20:21], v[24:25], v[20:21] op_sel:[1,0] op_sel_hi:[0,1]
	v_pk_fma_f32 v[12:13], v[24:25], v[12:13], v[34:35]
	v_pk_fma_f32 v[18:19], v[24:25], v[38:39], v[18:19]
	v_pk_fma_f32 v[22:23], v[24:25], v[22:23], v[40:41]
	v_pk_fma_f32 v[20:21], v[24:25], v[44:45], v[20:21]
	v_pk_fma_f32 v[12:13], v[48:49], v[36:37], v[12:13] op_sel_hi:[0,1,1]
	v_pk_fma_f32 v[14:15], v[48:49], v[14:15], v[18:19] op_sel_hi:[0,1,1]
	v_pk_fma_f32 v[18:19], v[48:49], v[42:43], v[22:23] op_sel_hi:[0,1,1]
	v_pk_fma_f32 v[16:17], v[48:49], v[16:17], v[20:21] op_sel_hi:[0,1,1]
	v_pk_mul_f32 v[12:13], v[12:13], v[26:27]
	v_pk_mul_f32 v[14:15], v[14:15], v[28:29]
	v_pk_mul_f32 v[18:19], v[18:19], v[10:11]
	v_pk_mul_f32 v[16:17], v[16:17], v[32:33]
	v_cvt_pk_bf16_f32 v10, v12, v13
	v_cvt_pk_bf16_f32 v11, v14, v15
	v_cvt_pk_bf16_f32 v12, v18, v19
	v_cvt_pk_bf16_f32 v13, v16, v17
	global_store_dwordx4 v[30:31], v[10:13], off
	s_waitcnt vmcnt(20)
	v_and_b32_e32 v87, 0xffff0000, v70
	v_lshlrev_b32_e32 v86, 16, v70
	s_waitcnt vmcnt(17)
	v_max3_f32 v108, v61, v106, v107
	v_sub_f32_e32 v61, v61, v108
	v_and_b32_e32 v89, 0xffff0000, v71
	s_waitcnt vmcnt(14)
	v_and_b32_e32 v103, 0xffff0000, v84
	v_lshlrev_b32_e32 v102, 16, v84
	v_sub_f32_e32 v84, v106, v108
	v_lshlrev_b32_e32 v88, 16, v71
	v_and_b32_e32 v71, 0xffff0000, v72
	v_lshlrev_b32_e32 v70, 16, v72
	v_and_b32_e32 v93, 0xffff0000, v73
	v_lshlrev_b32_e32 v92, 16, v73
	v_and_b32_e32 v73, 0xffff0000, v74
	v_lshlrev_b32_e32 v72, 16, v78
	v_and_b32_e32 v95, 0xffff0000, v78
	v_lshlrev_b32_e32 v94, 16, v74
	v_and_b32_e32 v97, 0xffff0000, v82
	v_lshlrev_b32_e32 v96, 16, v82
	v_and_b32_e32 v99, 0xffff0000, v75
	v_lshlrev_b32_e32 v78, 16, v75
	v_and_b32_e32 v75, 0xffff0000, v83
	v_lshlrev_b32_e32 v74, 16, v83
	v_and_b32_e32 v83, 0xffff0000, v76
	v_lshlrev_b32_e32 v82, 16, v80
	v_and_b32_e32 v101, 0xffff0000, v80
	v_lshlrev_b32_e32 v100, 16, v76
	v_and_b32_e32 v105, 0xffff0000, v77
	v_lshlrev_b32_e32 v80, 16, v77
	v_and_b32_e32 v77, 0xffff0000, v85
	v_lshlrev_b32_e32 v76, 16, v85
	v_sub_f32_e32 v85, v107, v108
	v_mul_f32_e32 v61, 0x3fb8aa3b, v61
	v_mul_f32_e32 v84, 0x3fb8aa3b, v84
	v_mul_f32_e32 v106, 0x3fb8aa3b, v85
	v_exp_f32_e32 v85, v61
	v_exp_f32_e32 v84, v84
	v_exp_f32_e32 v61, v106
	v_lshlrev_b32_e32 v98, 16, v79
	v_and_b32_e32 v79, 0xffff0000, v79
	v_add_f32_e32 v106, v85, v84
	v_add_f32_e32 v106, v61, v106
	v_div_scale_f32 v107, s[10:11], v106, v106, 1.0
	v_rcp_f32_e32 v109, v107
	v_div_scale_f32 v108, vcc, 1.0, v106, 1.0
	v_lshlrev_b32_e32 v104, 16, v81
	v_fma_f32 v110, -v107, v109, 1.0
	v_fmac_f32_e32 v109, v110, v109
	v_mul_f32_e32 v110, v108, v109
	v_fma_f32 v111, -v107, v110, v108
	v_fmac_f32_e32 v110, v111, v109
	v_fma_f32 v107, -v107, v110, v108
	v_div_fmas_f32 v107, v107, v109, v110
	v_div_fixup_f32 v106, v107, v106, 1.0
	v_and_b32_e32 v81, 0xffff0000, v81
	v_pk_mul_f32 v[84:85], v[84:85], v[106:107] op_sel_hi:[1,0]
	v_mul_f32_e32 v108, v61, v106
	v_pk_mul_f32 v[94:95], v[84:85], v[94:95] op_sel:[1,0] op_sel_hi:[0,1]
	v_pk_mul_f32 v[78:79], v[84:85], v[78:79] op_sel:[1,0] op_sel_hi:[0,1]
	v_pk_mul_f32 v[100:101], v[84:85], v[100:101] op_sel:[1,0] op_sel_hi:[0,1]
	v_pk_mul_f32 v[80:81], v[84:85], v[80:81] op_sel:[1,0] op_sel_hi:[0,1]
	v_pk_fma_f32 v[72:73], v[84:85], v[72:73], v[94:95]
	v_pk_fma_f32 v[78:79], v[84:85], v[98:99], v[78:79]
	v_pk_fma_f32 v[82:83], v[84:85], v[82:83], v[100:101]
	v_pk_fma_f32 v[80:81], v[84:85], v[104:105], v[80:81]
	v_pk_fma_f32 v[72:73], v[108:109], v[96:97], v[72:73] op_sel_hi:[0,1,1]
	v_pk_fma_f32 v[74:75], v[108:109], v[74:75], v[78:79] op_sel_hi:[0,1,1]
	v_pk_fma_f32 v[78:79], v[108:109], v[102:103], v[82:83] op_sel_hi:[0,1,1]
	v_pk_fma_f32 v[76:77], v[108:109], v[76:77], v[80:81] op_sel_hi:[0,1,1]
	v_pk_mul_f32 v[72:73], v[72:73], v[86:87]
	v_pk_mul_f32 v[74:75], v[74:75], v[88:89]
	v_pk_mul_f32 v[78:79], v[78:79], v[70:71]
	v_pk_mul_f32 v[76:77], v[76:77], v[92:93]
	v_cvt_pk_bf16_f32 v70, v72, v73
	v_cvt_pk_bf16_f32 v71, v74, v75
	v_cvt_pk_bf16_f32 v72, v78, v79
	v_cvt_pk_bf16_f32 v73, v76, v77
	global_store_dwordx4 v[90:91], v[70:73], off
	s_waitcnt vmcnt(13)
	v_and_b32_e32 v147, 0xffff0000, v130
	v_lshlrev_b32_e32 v146, 16, v130
	s_waitcnt vmcnt(10)
	v_max3_f32 v168, v121, v166, v167
	v_sub_f32_e32 v121, v121, v168
	v_and_b32_e32 v149, 0xffff0000, v131
	s_waitcnt vmcnt(7)
	v_and_b32_e32 v163, 0xffff0000, v144
	v_lshlrev_b32_e32 v162, 16, v144
	v_sub_f32_e32 v144, v166, v168
	v_lshlrev_b32_e32 v148, 16, v131
	v_and_b32_e32 v131, 0xffff0000, v132
	v_lshlrev_b32_e32 v130, 16, v132
	v_and_b32_e32 v153, 0xffff0000, v133
	v_lshlrev_b32_e32 v152, 16, v133
	v_and_b32_e32 v133, 0xffff0000, v134
	v_lshlrev_b32_e32 v132, 16, v138
	v_and_b32_e32 v155, 0xffff0000, v138
	v_lshlrev_b32_e32 v154, 16, v134
	v_and_b32_e32 v157, 0xffff0000, v142
	v_lshlrev_b32_e32 v156, 16, v142
	v_and_b32_e32 v159, 0xffff0000, v135
	v_lshlrev_b32_e32 v138, 16, v135
	v_and_b32_e32 v135, 0xffff0000, v143
	v_lshlrev_b32_e32 v134, 16, v143
	v_and_b32_e32 v143, 0xffff0000, v136
	v_lshlrev_b32_e32 v142, 16, v140
	v_and_b32_e32 v161, 0xffff0000, v140
	v_lshlrev_b32_e32 v160, 16, v136
	v_and_b32_e32 v165, 0xffff0000, v137
	v_lshlrev_b32_e32 v140, 16, v137
	v_and_b32_e32 v137, 0xffff0000, v145
	v_lshlrev_b32_e32 v136, 16, v145
	v_sub_f32_e32 v145, v167, v168
	v_mul_f32_e32 v121, 0x3fb8aa3b, v121
	v_mul_f32_e32 v144, 0x3fb8aa3b, v144
	v_mul_f32_e32 v166, 0x3fb8aa3b, v145
	v_exp_f32_e32 v145, v121
	v_exp_f32_e32 v144, v144
	v_exp_f32_e32 v121, v166
	v_lshlrev_b32_e32 v158, 16, v139
	v_and_b32_e32 v139, 0xffff0000, v139
	v_add_f32_e32 v166, v145, v144
	v_add_f32_e32 v166, v121, v166
	v_div_scale_f32 v167, s[10:11], v166, v166, 1.0
	v_rcp_f32_e32 v169, v167
	v_div_scale_f32 v168, vcc, 1.0, v166, 1.0
	v_lshlrev_b32_e32 v164, 16, v141
	v_fma_f32 v170, -v167, v169, 1.0
	v_fmac_f32_e32 v169, v170, v169
	v_mul_f32_e32 v170, v168, v169
	v_fma_f32 v171, -v167, v170, v168
	v_fmac_f32_e32 v170, v171, v169
	v_fma_f32 v167, -v167, v170, v168
	v_div_fmas_f32 v167, v167, v169, v170
	v_div_fixup_f32 v166, v167, v166, 1.0
	v_and_b32_e32 v141, 0xffff0000, v141
	v_pk_mul_f32 v[144:145], v[144:145], v[166:167] op_sel_hi:[1,0]
	v_mul_f32_e32 v168, v121, v166
	v_pk_mul_f32 v[154:155], v[144:145], v[154:155] op_sel:[1,0] op_sel_hi:[0,1]
	v_pk_mul_f32 v[138:139], v[144:145], v[138:139] op_sel:[1,0] op_sel_hi:[0,1]
	v_pk_mul_f32 v[160:161], v[144:145], v[160:161] op_sel:[1,0] op_sel_hi:[0,1]
	v_pk_mul_f32 v[140:141], v[144:145], v[140:141] op_sel:[1,0] op_sel_hi:[0,1]
	v_pk_fma_f32 v[132:133], v[144:145], v[132:133], v[154:155]
	v_pk_fma_f32 v[138:139], v[144:145], v[158:159], v[138:139]
	v_pk_fma_f32 v[142:143], v[144:145], v[142:143], v[160:161]
	v_pk_fma_f32 v[140:141], v[144:145], v[164:165], v[140:141]
	v_pk_fma_f32 v[132:133], v[168:169], v[156:157], v[132:133] op_sel_hi:[0,1,1]
	v_pk_fma_f32 v[134:135], v[168:169], v[134:135], v[138:139] op_sel_hi:[0,1,1]
	v_pk_fma_f32 v[138:139], v[168:169], v[162:163], v[142:143] op_sel_hi:[0,1,1]
	v_pk_fma_f32 v[136:137], v[168:169], v[136:137], v[140:141] op_sel_hi:[0,1,1]
	v_pk_mul_f32 v[132:133], v[132:133], v[146:147]
	v_pk_mul_f32 v[134:135], v[134:135], v[148:149]
	v_pk_mul_f32 v[138:139], v[138:139], v[130:131]
	v_pk_mul_f32 v[136:137], v[136:137], v[152:153]
	v_cvt_pk_bf16_f32 v130, v132, v133
	v_cvt_pk_bf16_f32 v131, v134, v135
	v_cvt_pk_bf16_f32 v132, v138, v139
	v_cvt_pk_bf16_f32 v133, v136, v137
	global_store_dwordx4 v[150:151], v[130:133], off
	s_waitcnt vmcnt(6)
	v_and_b32_e32 v207, 0xffff0000, v190
	v_lshlrev_b32_e32 v206, 16, v190
	s_waitcnt vmcnt(3)
	v_max3_f32 v228, v181, v226, v227
	v_sub_f32_e32 v181, v181, v228
	v_and_b32_e32 v209, 0xffff0000, v191
	s_waitcnt vmcnt(0)
	v_and_b32_e32 v223, 0xffff0000, v204
	v_lshlrev_b32_e32 v222, 16, v204
	v_sub_f32_e32 v204, v226, v228
	v_lshlrev_b32_e32 v208, 16, v191
	v_and_b32_e32 v191, 0xffff0000, v192
	v_lshlrev_b32_e32 v190, 16, v192
	v_and_b32_e32 v213, 0xffff0000, v193
	v_lshlrev_b32_e32 v212, 16, v193
	v_and_b32_e32 v193, 0xffff0000, v194
	v_lshlrev_b32_e32 v192, 16, v198
	v_and_b32_e32 v215, 0xffff0000, v198
	v_lshlrev_b32_e32 v214, 16, v194
	v_and_b32_e32 v217, 0xffff0000, v202
	v_lshlrev_b32_e32 v216, 16, v202
	v_and_b32_e32 v219, 0xffff0000, v195
	v_lshlrev_b32_e32 v198, 16, v195
	v_and_b32_e32 v195, 0xffff0000, v203
	v_lshlrev_b32_e32 v194, 16, v203
	v_and_b32_e32 v203, 0xffff0000, v196
	v_lshlrev_b32_e32 v202, 16, v200
	v_and_b32_e32 v221, 0xffff0000, v200
	v_lshlrev_b32_e32 v220, 16, v196
	v_and_b32_e32 v225, 0xffff0000, v197
	v_lshlrev_b32_e32 v200, 16, v197
	v_and_b32_e32 v197, 0xffff0000, v205
	v_lshlrev_b32_e32 v196, 16, v205
	v_sub_f32_e32 v205, v227, v228
	v_mul_f32_e32 v181, 0x3fb8aa3b, v181
	v_mul_f32_e32 v204, 0x3fb8aa3b, v204
	v_mul_f32_e32 v226, 0x3fb8aa3b, v205
	v_exp_f32_e32 v205, v181
	v_exp_f32_e32 v204, v204
	v_exp_f32_e32 v181, v226
	v_lshlrev_b32_e32 v218, 16, v199
	v_and_b32_e32 v199, 0xffff0000, v199
	v_add_f32_e32 v226, v205, v204
	v_add_f32_e32 v226, v181, v226
	v_div_scale_f32 v227, s[10:11], v226, v226, 1.0
	v_rcp_f32_e32 v229, v227
	v_div_scale_f32 v228, vcc, 1.0, v226, 1.0
	v_lshlrev_b32_e32 v224, 16, v201
	v_fma_f32 v230, -v227, v229, 1.0
	v_fmac_f32_e32 v229, v230, v229
	v_mul_f32_e32 v230, v228, v229
	v_fma_f32 v231, -v227, v230, v228
	v_fmac_f32_e32 v230, v231, v229
	v_fma_f32 v227, -v227, v230, v228
	v_div_fmas_f32 v227, v227, v229, v230
	v_div_fixup_f32 v226, v227, v226, 1.0
	v_and_b32_e32 v201, 0xffff0000, v201
	v_pk_mul_f32 v[204:205], v[204:205], v[226:227] op_sel_hi:[1,0]
	v_mul_f32_e32 v228, v181, v226
	v_pk_mul_f32 v[214:215], v[204:205], v[214:215] op_sel:[1,0] op_sel_hi:[0,1]
	v_pk_mul_f32 v[198:199], v[204:205], v[198:199] op_sel:[1,0] op_sel_hi:[0,1]
	v_pk_mul_f32 v[220:221], v[204:205], v[220:221] op_sel:[1,0] op_sel_hi:[0,1]
	v_pk_mul_f32 v[200:201], v[204:205], v[200:201] op_sel:[1,0] op_sel_hi:[0,1]
	v_pk_fma_f32 v[192:193], v[204:205], v[192:193], v[214:215]
	v_pk_fma_f32 v[198:199], v[204:205], v[218:219], v[198:199]
	v_pk_fma_f32 v[202:203], v[204:205], v[202:203], v[220:221]
	v_pk_fma_f32 v[200:201], v[204:205], v[224:225], v[200:201]
	v_pk_fma_f32 v[192:193], v[228:229], v[216:217], v[192:193] op_sel_hi:[0,1,1]
	v_pk_fma_f32 v[194:195], v[228:229], v[194:195], v[198:199] op_sel_hi:[0,1,1]
	v_pk_fma_f32 v[198:199], v[228:229], v[222:223], v[202:203] op_sel_hi:[0,1,1]
	v_pk_fma_f32 v[196:197], v[228:229], v[196:197], v[200:201] op_sel_hi:[0,1,1]
	v_pk_mul_f32 v[192:193], v[192:193], v[206:207]
	v_pk_mul_f32 v[194:195], v[194:195], v[208:209]
	v_pk_mul_f32 v[198:199], v[198:199], v[190:191]
	v_pk_mul_f32 v[196:197], v[196:197], v[212:213]
	v_cvt_pk_bf16_f32 v190, v192, v193
	v_cvt_pk_bf16_f32 v191, v194, v195
	v_cvt_pk_bf16_f32 v192, v198, v199
	v_cvt_pk_bf16_f32 v193, v196, v197
	global_store_dwordx4 v[210:211], v[190:193], off
	s_branch .Lmg_top
